# GEMM1 epilogue: the 88 flat_store (address space unknown to hipcc) rewritten as global_store with the same operands
# speedup vs baseline: 1.0147x; 1.0092x over previous
; __device__ __forceinline__ uint2 pk4(f32x4 v) { return make_uint2(pk2(v[0], v[1]), pk2(v[2], v[3])); }
; __device__ __forceinline__ void wave_store_rows(char* wsm, u16* gbase, const size_t ld, const f32x4 (&acc)[8][4], const int lane) {
;     ...
;   for (int hf = 0; hf < 2; hf++) {
; #pragma unroll
;     for (int m = 0; m < 4; m++)
; #pragma unroll
;       for (int n = 0; n < 4; n++) {
;         const int row = m * 16 + fr, chunk = n * 2 + (fq >> 1);
;         *(uint2*)(wsm + row * 128 + ((chunk ^ (fr & 7)) << 4) + (fq & 1) * 8) = pk4(acc[hf * 4 + m][n]);
;       }
; #pragma unroll
;     for (int i = 0; i < 8; i++) {
;       const int row = i * 8 + rr;
;       const uint4 v = *(const uint4*)(wsm + row * 128 + ((ch ^ (row & 7)) << 4));
;       __builtin_nontemporal_store(__builtin_bit_cast(u32x4_t, v), (u32x4_t*)(gbase + (size_t)(hf * 64 + row) * ld + ch * 8));
;     }
; __device__ void gemm1_phase(const Params& P, int layer, char* smem) {
;     ...
;     } else if (!mixed) {
;       wave_store_rows(wsm, p_proj + (size_t)rowb * INC + cw, INC, acc, lane);
.LBB0_129:
	s_movk_i32 s16, 0x1700
	v_cmp_ne_u32_e32 vcc, s16, v130
	s_and_saveexec_b64 s[16:17], vcc
	s_xor_b64 s[16:17], exec, s[16:17]
	s_cbranch_execz .LBB0_131
	v_mov_b64_e32 v[138:139], s[6:7]
	s_movk_i32 s18, 0x4680
	v_mad_i64_i32 v[138:139], s[18:19], v132, s18, v[138:139]
	v_mov_b32_e32 v131, v97
	v_lshl_add_u64 v[138:139], v[130:131], 1, v[138:139]
	v_lshrrev_b32_e32 v131, 3, v136
	v_and_b32_e32 v96, 8, v187
	v_and_b32_e32 v135, 7, v186
	v_add_u32_e32 v144, v146, v96
	v_bitop3_b32 v96, v131, v186, 7 bitop3:0x78
	v_lshlrev_b32_e32 v140, 7, v136
	v_lshlrev_b32_e32 v145, 4, v96
	v_lshlrev_b32_e32 v96, 4, v135
	v_lshrrev_b32_e32 v137, 5, v136
	v_and_b32_e32 v141, 0x780, v140
	v_lshl_add_u64 v[142:143], v[138:139], 0, v[96:97]
	v_lshlrev_b32_e32 v96, 7, v131
	v_add3_u32 v147, v146, v145, v96
	v_add_u32_e32 v96, v144, v141
	v_bitop3_b32 v141, v137, v186, 7 bitop3:0x78
	v_lshlrev_b32_e32 v141, 4, v141
	v_bitop3_b32 v145, v137, v135, 2 bitop3:0x36
	v_cvt_pk_bf16_f32 v138, v114, v115
	v_cvt_pk_bf16_f32 v139, v116, v117
	v_add_u32_e32 v150, v96, v141
	v_lshlrev_b32_e32 v145, 4, v145
	v_bitop3_b32 v148, v137, v135, 4 bitop3:0x36
	ds_write_b64 v150, v[138:139]
	v_cvt_pk_bf16_f32 v138, v118, v119
	v_cvt_pk_bf16_f32 v139, v120, v121
	v_add_u32_e32 v151, v96, v145
	v_lshlrev_b32_e32 v148, 4, v148
	v_bitop3_b32 v135, v137, v135, 6 bitop3:0x36
	ds_write_b64 v151, v[138:139]
	v_cvt_pk_bf16_f32 v138, v126, v127
	v_cvt_pk_bf16_f32 v139, v128, v129
	v_add_u32_e32 v152, v96, v148
	v_lshlrev_b32_e32 v135, 4, v135
	ds_write_b64 v152, v[138:139]
	v_cvt_pk_bf16_f32 v138, v122, v123
	v_cvt_pk_bf16_f32 v139, v124, v125
	v_add_u32_e32 v137, v96, v135
	ds_write_b64 v137, v[138:139]
	v_cvt_pk_bf16_f32 v138, v106, v107
	v_cvt_pk_bf16_f32 v139, v108, v109
	ds_write_b64 v150, v[138:139] offset:2048
	v_cvt_pk_bf16_f32 v138, v98, v99
	v_cvt_pk_bf16_f32 v139, v100, v101
	ds_write_b64 v151, v[138:139] offset:2048
	v_cvt_pk_bf16_f32 v138, v110, v111
	v_cvt_pk_bf16_f32 v139, v112, v113
	ds_write_b64 v152, v[138:139] offset:2048
	v_cvt_pk_bf16_f32 v138, v102, v103
	v_cvt_pk_bf16_f32 v139, v104, v105
	ds_write_b64 v137, v[138:139] offset:2048
	v_cvt_pk_bf16_f32 v138, v88, v89
	v_cvt_pk_bf16_f32 v139, v90, v91
	ds_write_b64 v150, v[138:139] offset:4096
	v_cvt_pk_bf16_f32 v138, v80, v81
	v_cvt_pk_bf16_f32 v139, v82, v83
	ds_write_b64 v151, v[138:139] offset:4096
	v_cvt_pk_bf16_f32 v138, v92, v93
	v_cvt_pk_bf16_f32 v139, v94, v95
	v_or_b32_e32 v96, 0x1800, v140
	ds_write_b64 v152, v[138:139] offset:4096
	v_cvt_pk_bf16_f32 v138, v84, v85
	v_cvt_pk_bf16_f32 v139, v86, v87
	v_add_u32_e32 v96, v144, v96
	ds_write_b64 v137, v[138:139] offset:4096
	v_cvt_pk_bf16_f32 v138, v72, v73
	v_cvt_pk_bf16_f32 v139, v74, v75
	v_add_u32_e32 v153, v96, v141
	ds_write_b64 v153, v[138:139]
	v_cvt_pk_bf16_f32 v138, v64, v65
	v_cvt_pk_bf16_f32 v139, v66, v67
	v_add_u32_e32 v154, v96, v145
	ds_write_b64 v154, v[138:139]
	v_cvt_pk_bf16_f32 v138, v76, v77
	v_cvt_pk_bf16_f32 v139, v78, v79
	v_add_u32_e32 v155, v96, v148
	ds_write_b64 v155, v[138:139]
	ds_read_b128 v[138:141], v147
	v_add_u32_e32 v135, v96, v135
	v_mul_u32_u24_e32 v96, 0x2340, v131
	v_cvt_pk_bf16_f32 v144, v68, v69
	v_cvt_pk_bf16_f32 v145, v70, v71
	v_lshlrev_b32_e32 v96, 1, v96
	ds_write_b64 v135, v[144:145]
	v_lshl_add_u64 v[144:145], v[142:143], 0, v[96:97]
	s_waitcnt lgkmcnt(1)
	global_store_dwordx4 v[144:145], v[138:141], off nt
	ds_read_b128 v[138:141], v147 offset:1024
	s_mov_b32 s18, 0x23000
	v_add_co_u32_e32 v148, vcc, s18, v144
	s_mov_b32 s18, 0x46000
	s_nop 0
	v_addc_co_u32_e32 v149, vcc, 0, v145, vcc
	s_waitcnt lgkmcnt(0)
	global_store_dwordx4 v[148:149], v[138:141], off offset:1024 nt
	ds_read_b128 v[138:141], v147 offset:2048
	v_add_co_u32_e32 v148, vcc, s18, v144
	s_mov_b32 s18, 0x69000
	s_nop 0
	v_addc_co_u32_e32 v149, vcc, 0, v145, vcc
	s_waitcnt lgkmcnt(0)
	global_store_dwordx4 v[148:149], v[138:141], off offset:2048 nt
	ds_read_b128 v[138:141], v147 offset:3072
	v_add_co_u32_e32 v148, vcc, s18, v144
	s_mov_b32 s18, 0x11a000
	s_nop 0
	v_addc_co_u32_e32 v149, vcc, 0, v145, vcc
	s_waitcnt lgkmcnt(0)
	global_store_dwordx4 v[148:149], v[138:141], off offset:3072 nt
	ds_read_b128 v[138:141], v147 offset:4096
	v_add_u32_e32 v148, 0x8d000, v96
	v_mov_b32_e32 v149, v97
	v_lshl_add_u64 v[148:149], v[142:143], 0, v[148:149]
	s_waitcnt lgkmcnt(0)
	global_store_dwordx4 v[148:149], v[138:141], off nt
	ds_read_b128 v[138:141], v147 offset:5120
	v_add_u32_e32 v148, 0xb0400, v96
	v_mov_b32_e32 v149, v97
	v_lshl_add_u64 v[148:149], v[142:143], 0, v[148:149]
	s_waitcnt lgkmcnt(0)
	global_store_dwordx4 v[148:149], v[138:141], off nt
	ds_read_b128 v[138:141], v147 offset:6144
	v_add_u32_e32 v148, 0xd3800, v96
	v_mov_b32_e32 v149, v97
	v_lshl_add_u64 v[148:149], v[142:143], 0, v[148:149]
	v_add_u32_e32 v96, 0xf6c00, v96
	s_waitcnt lgkmcnt(0)
	global_store_dwordx4 v[148:149], v[138:141], off nt
	ds_read_b128 v[138:141], v147 offset:7168
	v_lshl_add_u64 v[142:143], v[142:143], 0, v[96:97]
	s_waitcnt lgkmcnt(0)
; __device__ __forceinline__ uint2 pk4(f32x4 v) { return make_uint2(pk2(v[0], v[1]), pk2(v[2], v[3])); }
; __device__ __forceinline__ void wave_store_rows(char* wsm, u16* gbase, const size_t ld, const f32x4 (&acc)[8][4], const int lane) {
;     ...
;   for (int hf = 0; hf < 2; hf++) {
; #pragma unroll
;     for (int m = 0; m < 4; m++)
; #pragma unroll
;       for (int n = 0; n < 4; n++) {
;         const int row = m * 16 + fr, chunk = n * 2 + (fq >> 1);
;         *(uint2*)(wsm + row * 128 + ((chunk ^ (fr & 7)) << 4) + (fq & 1) * 8) = pk4(acc[hf * 4 + m][n]);
;       }
; #pragma unroll
;     for (int i = 0; i < 8; i++) {
;       const int row = i * 8 + rr;
;       const uint4 v = *(const uint4*)(wsm + row * 128 + ((ch ^ (row & 7)) << 4));
;       __builtin_nontemporal_store(__builtin_bit_cast(u32x4_t, v), (u32x4_t*)(gbase + (size_t)(hf * 64 + row) * ld + ch * 8));
;     }
; __device__ void gemm1_phase(const Params& P, int layer, char* smem) {
;     ...
; #pragma unroll
;       for (int n = 0; n < 4; n++) {
;         const int c0 = cw + n * 16 + fq * 4;
;         if (c0 < C_FB) {
; #pragma unroll
;           for (int m = 0; m < 8; m++) *(uint2*)(p_proj + (size_t)(row0 + m * 16) * INC + c0) = pk4(acc[m][n]);
	global_store_dwordx4 v[142:143], v[138:141], off nt
	s_nop 1
	v_cvt_pk_bf16_f32 v138, v56, v57
	v_cvt_pk_bf16_f32 v139, v58, v59
	ds_write_b64 v150, v[138:139]
	v_cvt_pk_bf16_f32 v138, v48, v49
	v_cvt_pk_bf16_f32 v139, v50, v51
	ds_write_b64 v151, v[138:139]
	v_cvt_pk_bf16_f32 v138, v60, v61
	v_cvt_pk_bf16_f32 v139, v62, v63
	ds_write_b64 v152, v[138:139]
	v_cvt_pk_bf16_f32 v138, v52, v53
	v_cvt_pk_bf16_f32 v139, v54, v55
	ds_write_b64 v137, v[138:139]
	v_cvt_pk_bf16_f32 v138, v40, v41
	v_cvt_pk_bf16_f32 v139, v42, v43
	ds_write_b64 v150, v[138:139] offset:2048
	v_cvt_pk_bf16_f32 v138, v32, v33
	v_cvt_pk_bf16_f32 v139, v34, v35
	ds_write_b64 v151, v[138:139] offset:2048
	v_cvt_pk_bf16_f32 v138, v44, v45
	v_cvt_pk_bf16_f32 v139, v46, v47
	ds_write_b64 v152, v[138:139] offset:2048
	v_cvt_pk_bf16_f32 v138, v36, v37
	v_cvt_pk_bf16_f32 v139, v38, v39
	ds_write_b64 v137, v[138:139] offset:2048
	v_cvt_pk_bf16_f32 v138, v24, v25
	v_cvt_pk_bf16_f32 v139, v26, v27
	ds_write_b64 v150, v[138:139] offset:4096
	v_cvt_pk_bf16_f32 v138, v8, v9
	v_cvt_pk_bf16_f32 v139, v10, v11
	ds_write_b64 v151, v[138:139] offset:4096
	v_cvt_pk_bf16_f32 v138, v28, v29
	v_cvt_pk_bf16_f32 v139, v30, v31
	ds_write_b64 v152, v[138:139] offset:4096
	v_cvt_pk_bf16_f32 v138, v12, v13
	v_cvt_pk_bf16_f32 v139, v14, v15
	ds_write_b64 v137, v[138:139] offset:4096
	v_cvt_pk_bf16_f32 v138, v16, v17
	v_cvt_pk_bf16_f32 v139, v18, v19
	ds_write_b64 v153, v[138:139]
	v_cvt_pk_bf16_f32 v138, v0, v1
	v_cvt_pk_bf16_f32 v139, v2, v3
	ds_write_b64 v154, v[138:139]
	v_cvt_pk_bf16_f32 v138, v20, v21
	v_cvt_pk_bf16_f32 v139, v22, v23
	ds_write_b64 v155, v[138:139]
	v_cvt_pk_bf16_f32 v138, v4, v5
	v_cvt_pk_bf16_f32 v139, v6, v7
	ds_write_b64 v135, v[138:139]
	ds_read_b128 v[138:141], v147
	v_add_co_u32_e32 v142, vcc, s18, v144
	s_mov_b32 s18, 0x13d000
	s_nop 0
	v_addc_co_u32_e32 v143, vcc, 0, v145, vcc
	s_waitcnt lgkmcnt(0)
	global_store_dwordx4 v[142:143], v[138:141], off nt
	ds_read_b128 v[138:141], v147 offset:1024
	v_add_co_u32_e32 v142, vcc, s18, v144
	s_mov_b32 s18, 0x160000
	s_nop 0
	v_addc_co_u32_e32 v143, vcc, 0, v145, vcc
	s_waitcnt lgkmcnt(0)
	global_store_dwordx4 v[142:143], v[138:141], off offset:1024 nt
	ds_read_b128 v[138:141], v147 offset:2048
	v_add_co_u32_e32 v142, vcc, s18, v144
	s_mov_b32 s18, 0x183000
	s_nop 0
	v_addc_co_u32_e32 v143, vcc, 0, v145, vcc
	s_waitcnt lgkmcnt(0)
	global_store_dwordx4 v[142:143], v[138:141], off offset:2048 nt
	ds_read_b128 v[138:141], v147 offset:3072
	v_add_co_u32_e32 v142, vcc, s18, v144
	s_mov_b32 s18, 0x1a7000
	s_nop 0
	v_addc_co_u32_e32 v143, vcc, 0, v145, vcc
	s_waitcnt lgkmcnt(0)
	global_store_dwordx4 v[142:143], v[138:141], off offset:3072 nt
	ds_read_b128 v[138:141], v147 offset:4096
	v_add_co_u32_e32 v142, vcc, s18, v144
	s_nop 1
	v_addc_co_u32_e32 v143, vcc, 0, v145, vcc
	s_waitcnt lgkmcnt(0)
	global_store_dwordx4 v[142:143], v[138:141], off nt
	ds_read_b128 v[138:141], v147 offset:5120
	v_add_co_u32_e32 v142, vcc, 0x1ca000, v144
	s_nop 1
	v_addc_co_u32_e32 v143, vcc, 0, v145, vcc
	s_waitcnt lgkmcnt(0)
	global_store_dwordx4 v[142:143], v[138:141], off offset:1024 nt
	ds_read_b128 v[138:141], v147 offset:6144
	v_add_co_u32_e32 v142, vcc, 0x1ed000, v144
	s_nop 1
	v_addc_co_u32_e32 v143, vcc, 0, v145, vcc
	s_waitcnt lgkmcnt(0)
	global_store_dwordx4 v[142:143], v[138:141], off offset:2048 nt
	ds_read_b128 v[138:141], v147 offset:7168
	v_add_co_u32_e32 v142, vcc, 0x210000, v144
	s_nop 1
	v_addc_co_u32_e32 v143, vcc, 0, v145, vcc
	s_waitcnt lgkmcnt(0)
	global_store_dwordx4 v[142:143], v[138:141], off offset:3072 nt
.LBB0_131:
	s_andn2_saveexec_b64 s[16:17], s[16:17]
	s_cbranch_execz .LBB0_133
	v_lshlrev_b32_e32 v96, 3, v133
	v_lshl_add_u64 v[138:139], s[6:7], 0, v[96:97]
	s_mov_b64 s[18:19], 0x2e00
	v_lshl_add_u64 v[140:141], v[138:139], 0, s[18:19]
	s_movk_i32 s26, 0x4680
	v_cvt_pk_bf16_f32 v142, v114, v115
	v_cvt_pk_bf16_f32 v143, v116, v117
	v_mad_i64_i32 v[144:145], s[18:19], v134, s26, v[140:141]
	global_store_dwordx2 v[144:145], v[142:143], off
	v_or_b32_e32 v144, 16, v134
	v_cvt_pk_bf16_f32 v142, v106, v107
	v_cvt_pk_bf16_f32 v143, v108, v109
	v_mad_i64_i32 v[148:149], s[18:19], v144, s26, v[140:141]
	global_store_dwordx2 v[148:149], v[142:143], off
	v_or_b32_e32 v148, 32, v134
	v_cvt_pk_bf16_f32 v142, v88, v89
	v_cvt_pk_bf16_f32 v143, v90, v91
	v_mad_i64_i32 v[150:151], s[18:19], v148, s26, v[140:141]
	global_store_dwordx2 v[150:151], v[142:143], off
	v_or_b32_e32 v150, 48, v134
	v_cvt_pk_bf16_f32 v142, v72, v73
	v_cvt_pk_bf16_f32 v143, v74, v75
	v_mad_i64_i32 v[152:153], s[18:19], v150, s26, v[140:141]
	global_store_dwordx2 v[152:153], v[142:143], off
	v_or_b32_e32 v152, 64, v134
	v_cvt_pk_bf16_f32 v142, v56, v57
	v_cvt_pk_bf16_f32 v143, v58, v59
	v_mad_i64_i32 v[154:155], s[18:19], v152, s26, v[140:141]
	global_store_dwordx2 v[154:155], v[142:143], off
	v_or_b32_e32 v154, 0x50, v134
	v_cvt_pk_bf16_f32 v142, v40, v41
	v_cvt_pk_bf16_f32 v143, v42, v43
	v_mad_i64_i32 v[156:157], s[18:19], v154, s26, v[140:141]
	global_store_dwordx2 v[156:157], v[142:143], off
	v_or_b32_e32 v156, 0x60, v134
	v_cvt_pk_bf16_f32 v142, v24, v25
	v_cvt_pk_bf16_f32 v143, v26, v27
	v_mad_i64_i32 v[158:159], s[18:19], v156, s26, v[140:141]
	global_store_dwordx2 v[158:159], v[142:143], off
	v_or_b32_e32 v158, 0x70, v134
	v_cvt_pk_bf16_f32 v142, v16, v17
	v_cvt_pk_bf16_f32 v143, v18, v19
	v_mad_i64_i32 v[140:141], s[18:19], v158, s26, v[140:141]
; __device__ __forceinline__ uint2 pk4(f32x4 v) { return make_uint2(pk2(v[0], v[1]), pk2(v[2], v[3])); }
; __device__ void gemm1_phase(const Params& P, int layer, char* smem) {
;     ...
; #pragma unroll
;       for (int n = 0; n < 4; n++) {
;         const int c0 = cw + n * 16 + fq * 4;
;         if (c0 < C_FB) {
; #pragma unroll
;           for (int m = 0; m < 8; m++) *(uint2*)(p_proj + (size_t)(row0 + m * 16) * INC + c0) = pk4(acc[m][n]);
;         } else {
; #pragma unroll
;           for (int m = 0; m < 8; m++)
;             *(float4*)(P.flog + (size_t)(row0 + m * 16) * 16 + (c0 - C_FB)) = make_float4(acc[m][n][0], acc[m][n][1], acc[m][n][2], acc[m][n][3]);
;         }
	v_ashrrev_i32_e32 v135, 31, v134
	v_ashrrev_i32_e32 v145, 31, v144
	v_ashrrev_i32_e32 v149, 31, v148
	v_ashrrev_i32_e32 v151, 31, v150
	v_ashrrev_i32_e32 v153, 31, v152
	v_ashrrev_i32_e32 v155, 31, v154
	v_ashrrev_i32_e32 v157, 31, v156
	v_ashrrev_i32_e32 v159, 31, v158
	global_store_dwordx2 v[140:141], v[142:143], off
	s_mov_b64 s[18:19], 0x2e20
	v_lshl_add_u64 v[140:141], v[138:139], 0, s[18:19]
	v_cvt_pk_bf16_f32 v142, v118, v119
	v_cvt_pk_bf16_f32 v143, v120, v121
	v_mad_i64_i32 v[160:161], s[18:19], v134, s26, v[140:141]
	global_store_dwordx2 v[160:161], v[142:143], off
	v_cvt_pk_bf16_f32 v142, v98, v99
	v_cvt_pk_bf16_f32 v143, v100, v101
	v_mad_i64_i32 v[160:161], s[18:19], v144, s26, v[140:141]
	global_store_dwordx2 v[160:161], v[142:143], off
	v_cvt_pk_bf16_f32 v142, v80, v81
	v_cvt_pk_bf16_f32 v143, v82, v83
	v_mad_i64_i32 v[160:161], s[18:19], v148, s26, v[140:141]
	global_store_dwordx2 v[160:161], v[142:143], off
	v_cvt_pk_bf16_f32 v142, v64, v65
	v_cvt_pk_bf16_f32 v143, v66, v67
	v_mad_i64_i32 v[160:161], s[18:19], v150, s26, v[140:141]
	global_store_dwordx2 v[160:161], v[142:143], off
	v_cvt_pk_bf16_f32 v142, v48, v49
	v_cvt_pk_bf16_f32 v143, v50, v51
	v_mad_i64_i32 v[160:161], s[18:19], v152, s26, v[140:141]
	global_store_dwordx2 v[160:161], v[142:143], off
	v_cvt_pk_bf16_f32 v142, v32, v33
	v_cvt_pk_bf16_f32 v143, v34, v35
	v_mad_i64_i32 v[160:161], s[18:19], v154, s26, v[140:141]
	global_store_dwordx2 v[160:161], v[142:143], off
	v_cvt_pk_bf16_f32 v142, v8, v9
	v_cvt_pk_bf16_f32 v143, v10, v11
	v_mad_i64_i32 v[160:161], s[18:19], v156, s26, v[140:141]
	global_store_dwordx2 v[160:161], v[142:143], off
	v_cvt_pk_bf16_f32 v142, v0, v1
	v_cvt_pk_bf16_f32 v143, v2, v3
	v_mad_i64_i32 v[140:141], s[18:19], v158, s26, v[140:141]
	global_store_dwordx2 v[140:141], v[142:143], off
	s_mov_b64 s[18:19], 0x2e40
	v_lshl_add_u64 v[138:139], v[138:139], 0, s[18:19]
	v_cvt_pk_bf16_f32 v140, v126, v127
	v_cvt_pk_bf16_f32 v141, v128, v129
	v_mad_i64_i32 v[142:143], s[18:19], v134, s26, v[138:139]
	global_store_dwordx2 v[142:143], v[140:141], off
	v_cvt_pk_bf16_f32 v140, v110, v111
	v_cvt_pk_bf16_f32 v141, v112, v113
	v_mad_i64_i32 v[142:143], s[18:19], v144, s26, v[138:139]
	global_store_dwordx2 v[142:143], v[140:141], off
	v_cvt_pk_bf16_f32 v140, v92, v93
	v_cvt_pk_bf16_f32 v141, v94, v95
	v_mad_i64_i32 v[142:143], s[18:19], v148, s26, v[138:139]
	global_store_dwordx2 v[142:143], v[140:141], off
	v_cvt_pk_bf16_f32 v140, v76, v77
	v_cvt_pk_bf16_f32 v141, v78, v79
	v_mad_i64_i32 v[142:143], s[18:19], v150, s26, v[138:139]
	global_store_dwordx2 v[142:143], v[140:141], off
	v_cvt_pk_bf16_f32 v140, v60, v61
	v_cvt_pk_bf16_f32 v141, v62, v63
	v_mad_i64_i32 v[142:143], s[18:19], v152, s26, v[138:139]
	global_store_dwordx2 v[142:143], v[140:141], off
	v_cvt_pk_bf16_f32 v140, v44, v45
	v_cvt_pk_bf16_f32 v141, v46, v47
	v_mad_i64_i32 v[142:143], s[18:19], v154, s26, v[138:139]
	global_store_dwordx2 v[142:143], v[140:141], off
	v_cvt_pk_bf16_f32 v140, v28, v29
	v_cvt_pk_bf16_f32 v141, v30, v31
	v_mad_i64_i32 v[142:143], s[18:19], v156, s26, v[138:139]
	global_store_dwordx2 v[142:143], v[140:141], off
	v_cvt_pk_bf16_f32 v140, v20, v21
	v_cvt_pk_bf16_f32 v141, v22, v23
	v_mad_i64_i32 v[138:139], s[18:19], v158, s26, v[138:139]
	v_readlane_b32 s26, v254, 52
	v_readlane_b32 s27, v254, 53
	global_store_dwordx2 v[138:139], v[140:141], off
	v_readlane_b32 s44, v253, 44
	v_lshlrev_b64 v[138:139], 6, v[134:135]
	v_readlane_b32 s45, v253, 45
	v_lshlrev_b32_e32 v96, 4, v133
	v_readlane_b32 s46, v253, 46
	v_lshl_add_u64 v[138:139], s[44:45], 0, v[138:139]
	v_lshl_add_u64 v[138:139], v[138:139], 0, v[96:97]
	global_store_dwordx4 v[138:139], v[122:125], off
	v_lshlrev_b64 v[138:139], 6, v[144:145]
	v_lshl_add_u64 v[138:139], s[44:45], 0, v[138:139]
	v_lshl_add_u64 v[138:139], v[138:139], 0, v[96:97]
	global_store_dwordx4 v[138:139], v[102:105], off
	v_lshlrev_b64 v[138:139], 6, v[148:149]
	v_lshl_add_u64 v[138:139], s[44:45], 0, v[138:139]
	v_lshl_add_u64 v[138:139], v[138:139], 0, v[96:97]
	global_store_dwordx4 v[138:139], v[84:87], off
	v_lshlrev_b64 v[138:139], 6, v[150:151]
	v_lshl_add_u64 v[138:139], s[44:45], 0, v[138:139]
	v_lshl_add_u64 v[138:139], v[138:139], 0, v[96:97]
	global_store_dwordx4 v[138:139], v[68:71], off
	v_lshlrev_b64 v[138:139], 6, v[152:153]
	v_lshl_add_u64 v[138:139], s[44:45], 0, v[138:139]
	v_lshl_add_u64 v[138:139], v[138:139], 0, v[96:97]
	global_store_dwordx4 v[138:139], v[52:55], off
	v_lshlrev_b64 v[138:139], 6, v[154:155]
	v_lshl_add_u64 v[138:139], s[44:45], 0, v[138:139]
	v_lshl_add_u64 v[138:139], v[138:139], 0, v[96:97]
	global_store_dwordx4 v[138:139], v[36:39], off
	v_lshlrev_b64 v[138:139], 6, v[156:157]
	v_lshl_add_u64 v[138:139], s[44:45], 0, v[138:139]
	v_lshl_add_u64 v[138:139], v[138:139], 0, v[96:97]
	global_store_dwordx4 v[138:139], v[12:15], off
	v_lshlrev_b64 v[138:139], 6, v[158:159]
	v_lshl_add_u64 v[138:139], s[44:45], 0, v[138:139]
	v_lshl_add_u64 v[138:139], v[138:139], 0, v[96:97]
	v_readlane_b32 s47, v253, 47
	v_readlane_b32 s48, v253, 48
	v_readlane_b32 s49, v253, 49
	v_readlane_b32 s50, v253, 50
	v_readlane_b32 s51, v253, 51
	v_readlane_b32 s52, v253, 52
	v_readlane_b32 s53, v253, 53
	v_readlane_b32 s54, v253, 54
	v_readlane_b32 s55, v253, 55
	v_readlane_b32 s56, v253, 56
	v_readlane_b32 s57, v253, 57
	v_readlane_b32 s58, v253, 58
	v_readlane_b32 s59, v253, 59
	global_store_dwordx4 v[138:139], v[4:7], off

; __device__ __forceinline__ uint2 pk4(f32x4 v) { return make_uint2(pk2(v[0], v[1]), pk2(v[2], v[3])); }
; __device__ __forceinline__ void wave_store_rows(char* wsm, u16* gbase, const size_t ld, const f32x4 (&acc)[8][4], const int lane) {
;     ...
;   for (int hf = 0; hf < 2; hf++) {
; #pragma unroll
;     for (int m = 0; m < 4; m++)
; #pragma unroll
;       for (int n = 0; n < 4; n++) {
;         const int row = m * 16 + fr, chunk = n * 2 + (fq >> 1);
;         *(uint2*)(wsm + row * 128 + ((chunk ^ (fr & 7)) << 4) + (fq & 1) * 8) = pk4(acc[hf * 4 + m][n]);
;       }
; #pragma unroll
;     for (int i = 0; i < 8; i++) {
;       const int row = i * 8 + rr;
;       const uint4 v = *(const uint4*)(wsm + row * 128 + ((ch ^ (row & 7)) << 4));
;       __builtin_nontemporal_store(__builtin_bit_cast(u32x4_t, v), (u32x4_t*)(gbase + (size_t)(hf * 64 + row) * ld + ch * 8));
;     }
; __device__ void gemm1_phase(const Params& P, int layer, char* smem) {
;     ...
;     } else if (rope_q || rope_k) {
;       if (rope_q) wave_store_rows(wsm, p_proj + (size_t)rowb * INC + cw, INC, acc, lane);
.LBB0_135:
	s_or_saveexec_b64 s[12:13], s[12:13]
	v_lshrrev_b32_e32 v147, 3, v136
	v_and_b32_e32 v152, 7, v186
	v_lshrrev_b32_e32 v96, 5, v136
	v_lshlrev_b32_e32 v131, 7, v136
	v_and_b32_e32 v153, 0x780, v131
	v_and_b32_e32 v156, 8, v187
	v_bitop3_b32 v157, v147, v186, 7 bitop3:0x78
	v_lshlrev_b32_e32 v155, 7, v147
	v_bitop3_b32 v154, v96, v186, 7 bitop3:0x78
	v_bitop3_b32 v151, v96, v152, 2 bitop3:0x36
	v_bitop3_b32 v150, v96, v152, 4 bitop3:0x36
	v_bitop3_b32 v149, v96, v152, 6 bitop3:0x36
	v_or_b32_e32 v148, 0x1800, v131
	s_xor_b64 exec, exec, s[12:13]
	s_cbranch_execz .LBB0_137
	v_mov_b64_e32 v[136:137], s[6:7]
	s_movk_i32 s14, 0x4680
	v_mad_i64_i32 v[136:137], s[14:15], v132, s14, v[136:137]
	v_ashrrev_i32_e32 v131, 31, v130
	v_lshl_add_u64 v[136:137], v[130:131], 1, v[136:137]
	v_add_u32_e32 v131, v146, v156
	v_lshlrev_b32_e32 v96, 4, v152
	v_lshl_add_u64 v[140:141], v[136:137], 0, v[96:97]
	v_add_u32_e32 v96, v131, v153
	v_lshlrev_b32_e32 v138, 4, v154
	v_cvt_pk_bf16_f32 v136, v114, v115
	v_cvt_pk_bf16_f32 v137, v116, v117
	v_add_u32_e32 v158, v96, v138
	v_lshlrev_b32_e32 v139, 4, v151
	ds_write_b64 v158, v[136:137]
	v_cvt_pk_bf16_f32 v136, v118, v119
	v_cvt_pk_bf16_f32 v137, v120, v121
	v_add_u32_e32 v159, v96, v139
	v_lshlrev_b32_e32 v142, 4, v150
	ds_write_b64 v159, v[136:137]
	v_cvt_pk_bf16_f32 v136, v126, v127
	v_cvt_pk_bf16_f32 v137, v128, v129
	v_add_u32_e32 v160, v96, v142
	v_lshlrev_b32_e32 v144, 4, v149
	ds_write_b64 v160, v[136:137]
	v_cvt_pk_bf16_f32 v136, v122, v123
	v_cvt_pk_bf16_f32 v137, v124, v125
	v_add_u32_e32 v161, v96, v144
	ds_write_b64 v161, v[136:137]
	v_cvt_pk_bf16_f32 v136, v106, v107
	v_cvt_pk_bf16_f32 v137, v108, v109
	ds_write_b64 v158, v[136:137] offset:2048
	v_cvt_pk_bf16_f32 v136, v98, v99
	v_cvt_pk_bf16_f32 v137, v100, v101
	ds_write_b64 v159, v[136:137] offset:2048
	v_cvt_pk_bf16_f32 v136, v110, v111
	v_cvt_pk_bf16_f32 v137, v112, v113
	ds_write_b64 v160, v[136:137] offset:2048
	v_cvt_pk_bf16_f32 v136, v102, v103
	v_cvt_pk_bf16_f32 v137, v104, v105
	ds_write_b64 v161, v[136:137] offset:2048
	v_cvt_pk_bf16_f32 v136, v88, v89
	v_cvt_pk_bf16_f32 v137, v90, v91
	ds_write_b64 v158, v[136:137] offset:4096
	v_cvt_pk_bf16_f32 v136, v80, v81
	v_cvt_pk_bf16_f32 v137, v82, v83
	ds_write_b64 v159, v[136:137] offset:4096
	v_cvt_pk_bf16_f32 v136, v92, v93
	v_cvt_pk_bf16_f32 v137, v94, v95
	ds_write_b64 v160, v[136:137] offset:4096
	v_cvt_pk_bf16_f32 v136, v84, v85
	v_cvt_pk_bf16_f32 v137, v86, v87
	v_add_u32_e32 v96, v131, v148
	ds_write_b64 v161, v[136:137] offset:4096
	v_cvt_pk_bf16_f32 v136, v72, v73
	v_cvt_pk_bf16_f32 v137, v74, v75
	v_add_u32_e32 v131, v96, v138
	v_lshlrev_b32_e32 v135, 4, v157
	ds_write_b64 v131, v[136:137]
	v_cvt_pk_bf16_f32 v136, v64, v65
	v_cvt_pk_bf16_f32 v137, v66, v67
	v_add_u32_e32 v162, v96, v139
	v_add3_u32 v135, v146, v135, v155
	ds_write_b64 v162, v[136:137]
	v_cvt_pk_bf16_f32 v136, v76, v77
	v_cvt_pk_bf16_f32 v137, v78, v79
	v_add_u32_e32 v163, v96, v142
	ds_write_b64 v163, v[136:137]
	ds_read_b128 v[136:139], v135
	v_add_u32_e32 v164, v96, v144
	v_mul_u32_u24_e32 v96, 0x2340, v147
	v_cvt_pk_bf16_f32 v142, v68, v69
	v_cvt_pk_bf16_f32 v143, v70, v71
	v_lshlrev_b32_e32 v96, 1, v96
	ds_write_b64 v164, v[142:143]
	v_lshl_add_u64 v[142:143], v[140:141], 0, v[96:97]
	s_waitcnt lgkmcnt(0)
	global_store_dwordx4 v[142:143], v[136:139], off nt
	ds_read_b128 v[136:139], v135 offset:1024
	s_mov_b32 s14, 0x23000
	v_add_co_u32_e32 v144, vcc, s14, v142
	s_mov_b32 s14, 0x46000
	s_nop 0
	v_addc_co_u32_e32 v145, vcc, 0, v143, vcc
	s_waitcnt lgkmcnt(0)
	global_store_dwordx4 v[144:145], v[136:139], off offset:1024 nt
	ds_read_b128 v[136:139], v135 offset:2048
	v_add_co_u32_e32 v144, vcc, s14, v142
	s_mov_b32 s14, 0x69000
	s_nop 0
	v_addc_co_u32_e32 v145, vcc, 0, v143, vcc
	s_waitcnt lgkmcnt(0)
	global_store_dwordx4 v[144:145], v[136:139], off offset:2048 nt
	ds_read_b128 v[136:139], v135 offset:3072
	v_add_co_u32_e32 v144, vcc, s14, v142
	s_mov_b32 s14, 0x11a000
	s_nop 0
	v_addc_co_u32_e32 v145, vcc, 0, v143, vcc
	s_waitcnt lgkmcnt(0)
	global_store_dwordx4 v[144:145], v[136:139], off offset:3072 nt
	ds_read_b128 v[136:139], v135 offset:4096
	v_add_u32_e32 v144, 0x8d000, v96
	v_mov_b32_e32 v145, v97
	v_lshl_add_u64 v[144:145], v[140:141], 0, v[144:145]
	s_or_b64 s[0:1], s[0:1], exec
	s_waitcnt lgkmcnt(0)
	global_store_dwordx4 v[144:145], v[136:139], off nt
	ds_read_b128 v[136:139], v135 offset:5120
	v_add_u32_e32 v144, 0xb0400, v96
	v_mov_b32_e32 v145, v97
	v_lshl_add_u64 v[144:145], v[140:141], 0, v[144:145]
	s_waitcnt lgkmcnt(0)
	global_store_dwordx4 v[144:145], v[136:139], off nt
	ds_read_b128 v[136:139], v135 offset:6144
	v_add_u32_e32 v144, 0xd3800, v96
	v_mov_b32_e32 v145, v97
	v_lshl_add_u64 v[144:145], v[140:141], 0, v[144:145]
	v_add_u32_e32 v96, 0xf6c00, v96
	s_waitcnt lgkmcnt(0)
	global_store_dwordx4 v[144:145], v[136:139], off nt
	ds_read_b128 v[136:139], v135 offset:7168
	v_lshl_add_u64 v[140:141], v[140:141], 0, v[96:97]
	s_waitcnt lgkmcnt(0)
; __device__ __forceinline__ uint2 pk4(f32x4 v) { return make_uint2(pk2(v[0], v[1]), pk2(v[2], v[3])); }
; __device__ __forceinline__ void wave_store_rows(char* wsm, u16* gbase, const size_t ld, const f32x4 (&acc)[8][4], const int lane) {
;     ...
;   for (int hf = 0; hf < 2; hf++) {
; #pragma unroll
;     for (int m = 0; m < 4; m++)
; #pragma unroll
;       for (int n = 0; n < 4; n++) {
;         const int row = m * 16 + fr, chunk = n * 2 + (fq >> 1);
;         *(uint2*)(wsm + row * 128 + ((chunk ^ (fr & 7)) << 4) + (fq & 1) * 8) = pk4(acc[hf * 4 + m][n]);
;       }
; #pragma unroll
;     for (int i = 0; i < 8; i++) {
;       const int row = i * 8 + rr;
;       const uint4 v = *(const uint4*)(wsm + row * 128 + ((ch ^ (row & 7)) << 4));
;       __builtin_nontemporal_store(__builtin_bit_cast(u32x4_t, v), (u32x4_t*)(gbase + (size_t)(hf * 64 + row) * ld + ch * 8));
;     }
; __device__ void gemm1_phase(const Params& P, int layer, char* smem) {
;     ...
;       for (int m = 0; m < 8; m++) {
;         const int tt = (row0 + m * 16) & (TSEQ - 1);
; #pragma unroll
;         for (int n = 0; n < 2; n++) {
;           const float4 c = *(const float4*)(P.ropec + tt * 32 + n * 16 + fq * 4);
;           const float4 sn = *(const float4*)(P.ropes + tt * 32 + n * 16 + fq * 4);
;           const f32x4 x1 = acc[m][n], x2 = acc[m][n + 2];
;           f32x4 r1, r2;
;           r1[0] = x1[0] * c.x - x2[0] * sn.x; r2[0] = x2[0] * c.x + x1[0] * sn.x;
;           r1[1] = x1[1] * c.y - x2[1] * sn.y; r2[1] = x2[1] * c.y + x1[1] * sn.y;
;           r1[2] = x1[2] * c.z - x2[2] * sn.z; r2[2] = x2[2] * c.z + x1[2] * sn.z;
;           r1[3] = x1[3] * c.w - x2[3] * sn.w; r2[3] = x2[3] * c.w + x1[3] * sn.w;
;           acc[m][n] = r1; acc[m][n + 2] = r2;
;         }
;       }
	global_store_dwordx4 v[140:141], v[136:139], off nt
	s_nop 1
	v_cvt_pk_bf16_f32 v136, v56, v57
	v_cvt_pk_bf16_f32 v137, v58, v59
	ds_write_b64 v158, v[136:137]
	v_cvt_pk_bf16_f32 v136, v48, v49
	v_cvt_pk_bf16_f32 v137, v50, v51
	ds_write_b64 v159, v[136:137]
	v_cvt_pk_bf16_f32 v136, v60, v61
	v_cvt_pk_bf16_f32 v137, v62, v63
	ds_write_b64 v160, v[136:137]
	v_cvt_pk_bf16_f32 v136, v52, v53
	v_cvt_pk_bf16_f32 v137, v54, v55
	ds_write_b64 v161, v[136:137]
	v_cvt_pk_bf16_f32 v136, v40, v41
	v_cvt_pk_bf16_f32 v137, v42, v43
	ds_write_b64 v158, v[136:137] offset:2048
	v_cvt_pk_bf16_f32 v136, v32, v33
	v_cvt_pk_bf16_f32 v137, v34, v35
	ds_write_b64 v159, v[136:137] offset:2048
	v_cvt_pk_bf16_f32 v136, v44, v45
	v_cvt_pk_bf16_f32 v137, v46, v47
	ds_write_b64 v160, v[136:137] offset:2048
	v_cvt_pk_bf16_f32 v136, v36, v37
	v_cvt_pk_bf16_f32 v137, v38, v39
	ds_write_b64 v161, v[136:137] offset:2048
	v_cvt_pk_bf16_f32 v136, v24, v25
	v_cvt_pk_bf16_f32 v137, v26, v27
	ds_write_b64 v158, v[136:137] offset:4096
	v_cvt_pk_bf16_f32 v136, v8, v9
	v_cvt_pk_bf16_f32 v137, v10, v11
	ds_write_b64 v159, v[136:137] offset:4096
	v_cvt_pk_bf16_f32 v136, v28, v29
	v_cvt_pk_bf16_f32 v137, v30, v31
	ds_write_b64 v160, v[136:137] offset:4096
	v_cvt_pk_bf16_f32 v136, v12, v13
	v_cvt_pk_bf16_f32 v137, v14, v15
	ds_write_b64 v161, v[136:137] offset:4096
	v_cvt_pk_bf16_f32 v136, v16, v17
	v_cvt_pk_bf16_f32 v137, v18, v19
	ds_write_b64 v131, v[136:137]
	v_cvt_pk_bf16_f32 v136, v0, v1
	v_cvt_pk_bf16_f32 v137, v2, v3
	ds_write_b64 v162, v[136:137]
	v_cvt_pk_bf16_f32 v136, v20, v21
	v_cvt_pk_bf16_f32 v137, v22, v23
	ds_write_b64 v163, v[136:137]
	v_cvt_pk_bf16_f32 v136, v4, v5
	v_cvt_pk_bf16_f32 v137, v6, v7
	ds_write_b64 v164, v[136:137]
	ds_read_b128 v[136:139], v135
	v_add_co_u32_e32 v140, vcc, s14, v142
	s_mov_b32 s14, 0x13d000
	s_nop 0
	v_addc_co_u32_e32 v141, vcc, 0, v143, vcc
	s_waitcnt lgkmcnt(0)
	global_store_dwordx4 v[140:141], v[136:139], off nt
	ds_read_b128 v[136:139], v135 offset:1024
	v_add_co_u32_e32 v140, vcc, s14, v142
	s_mov_b32 s14, 0x160000
	s_nop 0
	v_addc_co_u32_e32 v141, vcc, 0, v143, vcc
	s_waitcnt lgkmcnt(0)
	global_store_dwordx4 v[140:141], v[136:139], off offset:1024 nt
	ds_read_b128 v[136:139], v135 offset:2048
	v_add_co_u32_e32 v140, vcc, s14, v142
	s_mov_b32 s14, 0x183000
	s_nop 0
	v_addc_co_u32_e32 v141, vcc, 0, v143, vcc
	s_waitcnt lgkmcnt(0)
	global_store_dwordx4 v[140:141], v[136:139], off offset:2048 nt
	ds_read_b128 v[136:139], v135 offset:3072
	v_add_co_u32_e32 v140, vcc, s14, v142
	s_mov_b32 s14, 0x1a7000
	s_nop 0
	v_addc_co_u32_e32 v141, vcc, 0, v143, vcc
	s_waitcnt lgkmcnt(0)
	global_store_dwordx4 v[140:141], v[136:139], off offset:3072 nt
	ds_read_b128 v[136:139], v135 offset:4096
	v_add_co_u32_e32 v140, vcc, s14, v142
	s_nop 1
	v_addc_co_u32_e32 v141, vcc, 0, v143, vcc
	s_waitcnt lgkmcnt(0)
	global_store_dwordx4 v[140:141], v[136:139], off nt
	ds_read_b128 v[136:139], v135 offset:5120
	v_add_co_u32_e32 v140, vcc, 0x1ca000, v142
	s_nop 1
	v_addc_co_u32_e32 v141, vcc, 0, v143, vcc
	s_waitcnt lgkmcnt(0)
	global_store_dwordx4 v[140:141], v[136:139], off offset:1024 nt
	ds_read_b128 v[136:139], v135 offset:6144
	v_add_co_u32_e32 v140, vcc, 0x1ed000, v142
	s_nop 1
	v_addc_co_u32_e32 v141, vcc, 0, v143, vcc
	s_waitcnt lgkmcnt(0)
	global_store_dwordx4 v[140:141], v[136:139], off offset:2048 nt
	ds_read_b128 v[136:139], v135 offset:7168
	v_add_co_u32_e32 v140, vcc, 0x210000, v142
	s_nop 1
	v_addc_co_u32_e32 v141, vcc, 0, v143, vcc
	s_waitcnt lgkmcnt(0)
	global_store_dwordx4 v[140:141], v[136:139], off offset:3072 nt
.LBB0_137:
	s_or_b64 exec, exec, s[12:13]
	s_and_b64 exec, exec, s[0:1]
	s_cbranch_execz .LBB0_113
	v_lshlrev_b32_e32 v96, 4, v133
	v_lshl_add_u64 v[136:137], s[82:83], 0, v[96:97]
	v_lshl_add_u64 v[138:139], s[84:85], 0, v[96:97]
	v_lshlrev_b32_e32 v96, 7, v134
	v_and_b32_e32 v96, 0x3c780, v96
	v_lshl_add_u64 v[144:145], v[136:137], 0, v[96:97]
	v_lshl_add_u64 v[162:163], v[138:139], 0, v[96:97]
	global_load_dwordx4 v[140:143], v[144:145], off
	global_load_dwordx4 v[158:161], v[162:163], off
	v_ashrrev_i32_e32 v133, 31, v132
	s_waitcnt vmcnt(0)
	v_pk_mul_f32 v[134:135], v[114:115], v[158:159]
	s_nop 0
	v_pk_fma_f32 v[134:135], v[126:127], v[140:141], v[134:135]
	v_pk_mul_f32 v[126:127], v[126:127], v[158:159]
	s_nop 0
	v_pk_fma_f32 v[126:127], v[114:115], v[140:141], v[126:127] neg_lo:[0,0,1] neg_hi:[0,0,1]
	v_pk_mul_f32 v[114:115], v[116:117], v[160:161]
	s_nop 0
	v_pk_fma_f32 v[114:115], v[128:129], v[142:143], v[114:115]
	v_pk_mul_f32 v[128:129], v[128:129], v[160:161]
	s_nop 0
	v_pk_fma_f32 v[116:117], v[116:117], v[142:143], v[128:129] neg_lo:[0,0,1] neg_hi:[0,0,1]
	global_load_dwordx4 v[140:143], v[144:145], off offset:64
	global_load_dwordx4 v[158:161], v[162:163], off offset:64
	s_waitcnt vmcnt(0)
	v_pk_mul_f32 v[128:129], v[118:119], v[158:159]
	s_nop 0
	v_pk_fma_f32 v[128:129], v[122:123], v[140:141], v[128:129]
	v_pk_mul_f32 v[122:123], v[122:123], v[158:159]
	s_nop 0
	v_pk_fma_f32 v[122:123], v[118:119], v[140:141], v[122:123] neg_lo:[0,0,1] neg_hi:[0,0,1]
	v_pk_mul_f32 v[118:119], v[120:121], v[160:161]
	s_nop 0
	v_pk_fma_f32 v[118:119], v[124:125], v[142:143], v[118:119]
	v_pk_mul_f32 v[124:125], v[124:125], v[160:161]
	s_nop 0
	v_pk_fma_f32 v[120:121], v[120:121], v[142:143], v[124:125] neg_lo:[0,0,1] neg_hi:[0,0,1]
	global_load_dwordx4 v[140:143], v[144:145], off offset:2048
	global_load_dwordx4 v[158:161], v[162:163], off offset:2048
	s_waitcnt vmcnt(0)
; __device__ void gemm1_phase(const Params& P, int layer, char* smem) {
;     ...
;       for (int m = 0; m < 8; m++) {
;         const int tt = (row0 + m * 16) & (TSEQ - 1);
; #pragma unroll
;         for (int n = 0; n < 2; n++) {
;           const float4 c = *(const float4*)(P.ropec + tt * 32 + n * 16 + fq * 4);
;           const float4 sn = *(const float4*)(P.ropes + tt * 32 + n * 16 + fq * 4);
;           const f32x4 x1 = acc[m][n], x2 = acc[m][n + 2];
;           f32x4 r1, r2;
;           r1[0] = x1[0] * c.x - x2[0] * sn.x; r2[0] = x2[0] * c.x + x1[0] * sn.x;
;           r1[1] = x1[1] * c.y - x2[1] * sn.y; r2[1] = x2[1] * c.y + x1[1] * sn.y;
;           r1[2] = x1[2] * c.z - x2[2] * sn.z; r2[2] = x2[2] * c.z + x1[2] * sn.z;
;           r1[3] = x1[3] * c.w - x2[3] * sn.w; r2[3] = x2[3] * c.w + x1[3] * sn.w;
;           acc[m][n] = r1; acc[m][n + 2] = r2;
;         }
;       }
	v_pk_mul_f32 v[124:125], v[106:107], v[158:159]
	s_nop 0
	v_pk_fma_f32 v[124:125], v[110:111], v[140:141], v[124:125]
	v_pk_mul_f32 v[110:111], v[110:111], v[158:159]
	s_nop 0
	v_pk_fma_f32 v[110:111], v[106:107], v[140:141], v[110:111] neg_lo:[0,0,1] neg_hi:[0,0,1]
	v_pk_mul_f32 v[106:107], v[108:109], v[160:161]
	s_nop 0
	v_pk_fma_f32 v[106:107], v[112:113], v[142:143], v[106:107]
	v_pk_mul_f32 v[112:113], v[112:113], v[160:161]
	s_nop 0
	v_pk_fma_f32 v[108:109], v[108:109], v[142:143], v[112:113] neg_lo:[0,0,1] neg_hi:[0,0,1]
	global_load_dwordx4 v[140:143], v[144:145], off offset:2112
	global_load_dwordx4 v[158:161], v[162:163], off offset:2112
	s_waitcnt vmcnt(0)
	v_pk_mul_f32 v[112:113], v[98:99], v[158:159]
	s_nop 0
	v_pk_fma_f32 v[112:113], v[102:103], v[140:141], v[112:113]
	v_pk_mul_f32 v[102:103], v[102:103], v[158:159]
	s_nop 0
	v_pk_fma_f32 v[102:103], v[98:99], v[140:141], v[102:103] neg_lo:[0,0,1] neg_hi:[0,0,1]
	v_pk_mul_f32 v[98:99], v[100:101], v[160:161]
	s_nop 0
	v_pk_fma_f32 v[98:99], v[104:105], v[142:143], v[98:99]
	v_pk_mul_f32 v[104:105], v[104:105], v[160:161]
	s_nop 0
	v_pk_fma_f32 v[100:101], v[100:101], v[142:143], v[104:105] neg_lo:[0,0,1] neg_hi:[0,0,1]
	v_or_b32_e32 v104, 0x1000, v96
	v_mov_b32_e32 v105, v97
	v_lshl_add_u64 v[144:145], v[136:137], 0, v[104:105]
	v_lshl_add_u64 v[162:163], v[138:139], 0, v[104:105]
	global_load_dwordx4 v[140:143], v[144:145], off
	global_load_dwordx4 v[158:161], v[162:163], off
	s_waitcnt vmcnt(0)
	v_pk_mul_f32 v[104:105], v[88:89], v[158:159]
	s_nop 0
	v_pk_fma_f32 v[104:105], v[92:93], v[140:141], v[104:105]
	v_pk_mul_f32 v[92:93], v[92:93], v[158:159]
	s_nop 0
	v_pk_fma_f32 v[92:93], v[88:89], v[140:141], v[92:93] neg_lo:[0,0,1] neg_hi:[0,0,1]
	v_pk_mul_f32 v[88:89], v[90:91], v[160:161]
	s_nop 0
	v_pk_fma_f32 v[88:89], v[94:95], v[142:143], v[88:89]
	v_pk_mul_f32 v[94:95], v[94:95], v[160:161]
	s_nop 0
	v_pk_fma_f32 v[90:91], v[90:91], v[142:143], v[94:95] neg_lo:[0,0,1] neg_hi:[0,0,1]
	global_load_dwordx4 v[140:143], v[144:145], off offset:64
	global_load_dwordx4 v[158:161], v[162:163], off offset:64
	s_waitcnt vmcnt(0)
	v_pk_mul_f32 v[94:95], v[80:81], v[158:159]
	s_nop 0
	v_pk_fma_f32 v[94:95], v[84:85], v[140:141], v[94:95]
	v_pk_mul_f32 v[84:85], v[84:85], v[158:159]
	s_nop 0
	v_pk_fma_f32 v[84:85], v[80:81], v[140:141], v[84:85] neg_lo:[0,0,1] neg_hi:[0,0,1]
	v_pk_mul_f32 v[80:81], v[82:83], v[160:161]
	s_nop 0
	v_pk_fma_f32 v[80:81], v[86:87], v[142:143], v[80:81]
	v_pk_mul_f32 v[86:87], v[86:87], v[160:161]
	s_nop 0
	v_pk_fma_f32 v[82:83], v[82:83], v[142:143], v[86:87] neg_lo:[0,0,1] neg_hi:[0,0,1]
	v_or_b32_e32 v86, 0x1800, v96
	v_mov_b32_e32 v87, v97
	v_lshl_add_u64 v[144:145], v[136:137], 0, v[86:87]
	v_lshl_add_u64 v[162:163], v[138:139], 0, v[86:87]
	global_load_dwordx4 v[140:143], v[144:145], off
	global_load_dwordx4 v[158:161], v[162:163], off
	s_waitcnt vmcnt(0)
	v_pk_mul_f32 v[86:87], v[72:73], v[158:159]
	s_nop 0
	v_pk_fma_f32 v[86:87], v[76:77], v[140:141], v[86:87]
	v_pk_mul_f32 v[76:77], v[76:77], v[158:159]
	s_nop 0
	v_pk_fma_f32 v[76:77], v[72:73], v[140:141], v[76:77] neg_lo:[0,0,1] neg_hi:[0,0,1]
	v_pk_mul_f32 v[72:73], v[74:75], v[160:161]
	s_nop 0
	v_pk_fma_f32 v[72:73], v[78:79], v[142:143], v[72:73]
	v_pk_mul_f32 v[78:79], v[78:79], v[160:161]
	s_nop 0
	v_pk_fma_f32 v[78:79], v[74:75], v[142:143], v[78:79] neg_lo:[0,0,1] neg_hi:[0,0,1]
	global_load_dwordx4 v[140:143], v[144:145], off offset:64
	global_load_dwordx4 v[158:161], v[162:163], off offset:64
	s_waitcnt vmcnt(0)
	v_pk_mul_f32 v[74:75], v[64:65], v[158:159]
	s_nop 0
	v_pk_fma_f32 v[74:75], v[68:69], v[140:141], v[74:75]
	v_pk_mul_f32 v[68:69], v[68:69], v[158:159]
	s_nop 0
	v_pk_fma_f32 v[68:69], v[64:65], v[140:141], v[68:69] neg_lo:[0,0,1] neg_hi:[0,0,1]
	v_pk_mul_f32 v[64:65], v[66:67], v[160:161]
	s_nop 0
	v_pk_fma_f32 v[64:65], v[70:71], v[142:143], v[64:65]
	v_pk_mul_f32 v[70:71], v[70:71], v[160:161]
	s_nop 0
	v_pk_fma_f32 v[66:67], v[66:67], v[142:143], v[70:71] neg_lo:[0,0,1] neg_hi:[0,0,1]
	v_or_b32_e32 v70, 0x2000, v96
	v_mov_b32_e32 v71, v97
	v_lshl_add_u64 v[144:145], v[136:137], 0, v[70:71]
	v_lshl_add_u64 v[162:163], v[138:139], 0, v[70:71]
	global_load_dwordx4 v[140:143], v[144:145], off
	global_load_dwordx4 v[158:161], v[162:163], off
	s_waitcnt vmcnt(0)
	v_pk_mul_f32 v[70:71], v[56:57], v[158:159]
	s_nop 0
	v_pk_fma_f32 v[70:71], v[60:61], v[140:141], v[70:71]
	v_pk_mul_f32 v[60:61], v[60:61], v[158:159]
	s_nop 0
	v_pk_fma_f32 v[60:61], v[56:57], v[140:141], v[60:61] neg_lo:[0,0,1] neg_hi:[0,0,1]
	v_pk_mul_f32 v[56:57], v[58:59], v[160:161]
	s_nop 0
	v_pk_fma_f32 v[56:57], v[62:63], v[142:143], v[56:57]
	v_pk_mul_f32 v[62:63], v[62:63], v[160:161]
	s_nop 0
	v_pk_fma_f32 v[62:63], v[58:59], v[142:143], v[62:63] neg_lo:[0,0,1] neg_hi:[0,0,1]
	global_load_dwordx4 v[140:143], v[144:145], off offset:64
	global_load_dwordx4 v[158:161], v[162:163], off offset:64
	s_waitcnt vmcnt(0)
	v_pk_mul_f32 v[58:59], v[48:49], v[158:159]
	s_nop 0
	v_pk_fma_f32 v[58:59], v[52:53], v[140:141], v[58:59]
	v_pk_mul_f32 v[52:53], v[52:53], v[158:159]
	s_nop 0
	v_pk_fma_f32 v[52:53], v[48:49], v[140:141], v[52:53] neg_lo:[0,0,1] neg_hi:[0,0,1]
	v_pk_mul_f32 v[48:49], v[50:51], v[160:161]
	s_nop 0
	v_pk_fma_f32 v[48:49], v[54:55], v[142:143], v[48:49]
	v_pk_mul_f32 v[54:55], v[54:55], v[160:161]
	s_nop 0
	v_pk_fma_f32 v[50:51], v[50:51], v[142:143], v[54:55] neg_lo:[0,0,1] neg_hi:[0,0,1]
	v_or_b32_e32 v54, 0x2800, v96
	v_mov_b32_e32 v55, v97
	v_lshl_add_u64 v[144:145], v[136:137], 0, v[54:55]
	v_lshl_add_u64 v[162:163], v[138:139], 0, v[54:55]
	global_load_dwordx4 v[140:143], v[144:145], off
	global_load_dwordx4 v[158:161], v[162:163], off
	s_waitcnt vmcnt(0)
; __device__ __forceinline__ uint2 pk4(f32x4 v) { return make_uint2(pk2(v[0], v[1]), pk2(v[2], v[3])); }
; __device__ __forceinline__ void wave_store_rows(char* wsm, u16* gbase, const size_t ld, const f32x4 (&acc)[8][4], const int lane) {
;     ...
;   for (int hf = 0; hf < 2; hf++) {
; #pragma unroll
;     for (int m = 0; m < 4; m++)
; #pragma unroll
;       for (int n = 0; n < 4; n++) {
;         const int row = m * 16 + fr, chunk = n * 2 + (fq >> 1);
;         *(uint2*)(wsm + row * 128 + ((chunk ^ (fr & 7)) << 4) + (fq & 1) * 8) = pk4(acc[hf * 4 + m][n]);
; __device__ void gemm1_phase(const Params& P, int layer, char* smem) {
;     ...
;       for (int m = 0; m < 8; m++) {
;         const int tt = (row0 + m * 16) & (TSEQ - 1);
; #pragma unroll
;         for (int n = 0; n < 2; n++) {
;           const float4 c = *(const float4*)(P.ropec + tt * 32 + n * 16 + fq * 4);
;           const float4 sn = *(const float4*)(P.ropes + tt * 32 + n * 16 + fq * 4);
;           const f32x4 x1 = acc[m][n], x2 = acc[m][n + 2];
;           f32x4 r1, r2;
;           r1[0] = x1[0] * c.x - x2[0] * sn.x; r2[0] = x2[0] * c.x + x1[0] * sn.x;
;           r1[1] = x1[1] * c.y - x2[1] * sn.y; r2[1] = x2[1] * c.y + x1[1] * sn.y;
;           r1[2] = x1[2] * c.z - x2[2] * sn.z; r2[2] = x2[2] * c.z + x1[2] * sn.z;
;           r1[3] = x1[3] * c.w - x2[3] * sn.w; r2[3] = x2[3] * c.w + x1[3] * sn.w;
;           acc[m][n] = r1; acc[m][n + 2] = r2;
;         }
;       }
	v_pk_mul_f32 v[54:55], v[40:41], v[158:159]
	s_nop 0
	v_pk_fma_f32 v[54:55], v[44:45], v[140:141], v[54:55]
	v_pk_mul_f32 v[44:45], v[44:45], v[158:159]
	s_nop 0
	v_pk_fma_f32 v[44:45], v[40:41], v[140:141], v[44:45] neg_lo:[0,0,1] neg_hi:[0,0,1]
	v_pk_mul_f32 v[40:41], v[42:43], v[160:161]
	s_nop 0
	v_pk_fma_f32 v[40:41], v[46:47], v[142:143], v[40:41]
	v_pk_mul_f32 v[46:47], v[46:47], v[160:161]
	s_nop 0
	v_pk_fma_f32 v[46:47], v[42:43], v[142:143], v[46:47] neg_lo:[0,0,1] neg_hi:[0,0,1]
	global_load_dwordx4 v[140:143], v[144:145], off offset:64
	global_load_dwordx4 v[158:161], v[162:163], off offset:64
	s_waitcnt vmcnt(0)
	v_pk_mul_f32 v[42:43], v[32:33], v[158:159]
	s_nop 0
	v_pk_fma_f32 v[42:43], v[36:37], v[140:141], v[42:43]
	v_pk_mul_f32 v[36:37], v[36:37], v[158:159]
	s_nop 0
	v_pk_fma_f32 v[36:37], v[32:33], v[140:141], v[36:37] neg_lo:[0,0,1] neg_hi:[0,0,1]
	v_pk_mul_f32 v[32:33], v[34:35], v[160:161]
	s_nop 0
	v_pk_fma_f32 v[32:33], v[38:39], v[142:143], v[32:33]
	v_pk_mul_f32 v[38:39], v[38:39], v[160:161]
	s_nop 0
	v_pk_fma_f32 v[34:35], v[34:35], v[142:143], v[38:39] neg_lo:[0,0,1] neg_hi:[0,0,1]
	v_or_b32_e32 v38, 0x3000, v96
	v_mov_b32_e32 v39, v97
	v_lshl_add_u64 v[144:145], v[136:137], 0, v[38:39]
	v_lshl_add_u64 v[162:163], v[138:139], 0, v[38:39]
	global_load_dwordx4 v[140:143], v[144:145], off
	global_load_dwordx4 v[158:161], v[162:163], off
	v_or_b32_e32 v96, 0x3800, v96
	v_lshl_add_u64 v[138:139], v[138:139], 0, v[96:97]
	s_waitcnt vmcnt(0)
	v_pk_mul_f32 v[38:39], v[24:25], v[158:159]
	s_nop 0
	v_pk_fma_f32 v[38:39], v[28:29], v[140:141], v[38:39]
	v_pk_mul_f32 v[28:29], v[28:29], v[158:159]
	s_nop 0
	v_pk_fma_f32 v[28:29], v[24:25], v[140:141], v[28:29] neg_lo:[0,0,1] neg_hi:[0,0,1]
	v_pk_mul_f32 v[24:25], v[26:27], v[160:161]
	s_nop 0
	v_pk_fma_f32 v[24:25], v[30:31], v[142:143], v[24:25]
	v_pk_mul_f32 v[30:31], v[30:31], v[160:161]
	s_nop 0
	v_pk_fma_f32 v[26:27], v[26:27], v[142:143], v[30:31] neg_lo:[0,0,1] neg_hi:[0,0,1]
	global_load_dwordx4 v[142:145], v[144:145], off offset:64
	s_nop 0
	global_load_dwordx4 v[158:161], v[162:163], off offset:64
	s_waitcnt vmcnt(0)
	v_pk_mul_f32 v[30:31], v[8:9], v[158:159]
	s_nop 0
	v_pk_fma_f32 v[30:31], v[12:13], v[142:143], v[30:31]
	v_pk_mul_f32 v[12:13], v[12:13], v[158:159]
	v_lshl_add_u64 v[158:159], v[136:137], 0, v[96:97]
	v_pk_fma_f32 v[142:143], v[8:9], v[142:143], v[12:13] neg_lo:[0,0,1] neg_hi:[0,0,1]
	v_pk_mul_f32 v[8:9], v[10:11], v[160:161]
	v_lshlrev_b32_e32 v96, 4, v150
	v_pk_fma_f32 v[140:141], v[14:15], v[144:145], v[8:9]
	v_pk_mul_f32 v[8:9], v[14:15], v[160:161]
	s_nop 0
	v_pk_fma_f32 v[144:145], v[10:11], v[144:145], v[8:9] neg_lo:[0,0,1] neg_hi:[0,0,1]
	global_load_dwordx4 v[8:11], v[158:159], off
	global_load_dwordx4 v[12:15], v[138:139], off
	s_waitcnt vmcnt(0)
	v_pk_mul_f32 v[136:137], v[16:17], v[12:13]
	v_pk_mul_f32 v[12:13], v[20:21], v[12:13]
	v_pk_fma_f32 v[136:137], v[20:21], v[8:9], v[136:137]
	v_pk_fma_f32 v[20:21], v[16:17], v[8:9], v[12:13] neg_lo:[0,0,1] neg_hi:[0,0,1]
	v_pk_mul_f32 v[8:9], v[18:19], v[14:15]
	v_cvt_pk_bf16_f32 v20, v20, v21
	v_pk_fma_f32 v[16:17], v[22:23], v[10:11], v[8:9]
	v_pk_mul_f32 v[8:9], v[22:23], v[14:15]
	s_nop 0
	v_pk_fma_f32 v[18:19], v[18:19], v[10:11], v[8:9] neg_lo:[0,0,1] neg_hi:[0,0,1]
	global_load_dwordx4 v[8:11], v[158:159], off offset:64
	global_load_dwordx4 v[12:15], v[138:139], off offset:64
	v_lshl_add_u32 v139, v157, 4, v146
	v_add_u32_e32 v138, v139, v155
	v_cvt_pk_bf16_f32 v21, v18, v19
	s_waitcnt vmcnt(0)
	v_pk_mul_f32 v[22:23], v[0:1], v[12:13]
	s_nop 0
	v_pk_fma_f32 v[158:159], v[4:5], v[8:9], v[22:23]
	v_pk_mul_f32 v[4:5], v[4:5], v[12:13]
	v_lshlrev_b32_e32 v22, 4, v154
	v_pk_fma_f32 v[4:5], v[0:1], v[8:9], v[4:5] neg_lo:[0,0,1] neg_hi:[0,0,1]
	v_pk_mul_f32 v[0:1], v[2:3], v[14:15]
	v_lshlrev_b32_e32 v23, 4, v151
	v_pk_fma_f32 v[160:161], v[6:7], v[10:11], v[0:1]
	v_pk_mul_f32 v[0:1], v[6:7], v[14:15]
	v_add_u32_e32 v14, v146, v156
	v_pk_fma_f32 v[8:9], v[2:3], v[10:11], v[0:1] neg_lo:[0,0,1] neg_hi:[0,0,1]
	v_add_u32_e32 v12, v14, v153
	v_cvt_pk_bf16_f32 v11, v118, v119
	v_lshlrev_b32_e32 v118, 4, v149
	v_cvt_pk_bf16_f32 v0, v126, v127
	v_cvt_pk_bf16_f32 v1, v116, v117
	v_add_u32_e32 v116, v12, v22
	v_add_u32_e32 v117, v12, v23
	v_cvt_pk_bf16_f32 v7, v114, v115
	v_add_u32_e32 v114, v12, v96
	v_add_u32_e32 v115, v12, v118
	v_cvt_pk_bf16_f32 v12, v110, v111
	v_cvt_pk_bf16_f32 v13, v108, v109
	v_cvt_pk_bf16_f32 v2, v122, v123
	v_cvt_pk_bf16_f32 v3, v120, v121
	ds_write2st64_b64 v116, v[0:1], v[12:13] offset1:4
	v_cvt_pk_bf16_f32 v0, v102, v103
	v_cvt_pk_bf16_f32 v1, v100, v101
	v_cvt_pk_bf16_f32 v6, v134, v135
	ds_write2st64_b64 v117, v[2:3], v[0:1] offset1:4
	v_cvt_pk_bf16_f32 v0, v124, v125
	v_cvt_pk_bf16_f32 v1, v106, v107
	v_cvt_pk_bf16_f32 v10, v128, v129
	ds_write2st64_b64 v114, v[6:7], v[0:1] offset1:4
	v_cvt_pk_bf16_f32 v0, v112, v113
	v_cvt_pk_bf16_f32 v1, v98, v99
	ds_write2st64_b64 v115, v[10:11], v[0:1] offset1:4
	v_cvt_pk_bf16_f32 v0, v92, v93
	v_cvt_pk_bf16_f32 v1, v90, v91
	ds_write_b64 v116, v[0:1] offset:4096
	v_cvt_pk_bf16_f32 v0, v84, v85
	v_cvt_pk_bf16_f32 v1, v82, v83
	ds_write_b64 v117, v[0:1] offset:4096
	v_cvt_pk_bf16_f32 v0, v104, v105
	v_cvt_pk_bf16_f32 v1, v88, v89
	ds_write_b64 v114, v[0:1] offset:4096
	v_cvt_pk_bf16_f32 v0, v94, v95
	v_cvt_pk_bf16_f32 v1, v80, v81
	v_add_u32_e32 v2, v14, v148
	ds_write_b64 v115, v[0:1] offset:4096
	v_cvt_pk_bf16_f32 v0, v76, v77
	v_cvt_pk_bf16_f32 v1, v78, v79
	v_add_u32_e32 v76, v2, v22
	ds_write_b64 v76, v[0:1]
	v_cvt_pk_bf16_f32 v0, v68, v69
	v_cvt_pk_bf16_f32 v1, v66, v67
	v_add_u32_e32 v67, v2, v23
	ds_write_b64 v67, v[0:1]
; __device__ __forceinline__ uint2 pk4(f32x4 v) { return make_uint2(pk2(v[0], v[1]), pk2(v[2], v[3])); }
; __device__ __forceinline__ void wave_store_rows(char* wsm, u16* gbase, const size_t ld, const f32x4 (&acc)[8][4], const int lane) {
;     ...
;   for (int hf = 0; hf < 2; hf++) {
; #pragma unroll
;     for (int m = 0; m < 4; m++)
; #pragma unroll
;       for (int n = 0; n < 4; n++) {
;         const int row = m * 16 + fr, chunk = n * 2 + (fq >> 1);
;         *(uint2*)(wsm + row * 128 + ((chunk ^ (fr & 7)) << 4) + (fq & 1) * 8) = pk4(acc[hf * 4 + m][n]);
;       }
; #pragma unroll
;     for (int i = 0; i < 8; i++) {
;       const int row = i * 8 + rr;
;       const uint4 v = *(const uint4*)(wsm + row * 128 + ((ch ^ (row & 7)) << 4));
;       __builtin_nontemporal_store(__builtin_bit_cast(u32x4_t, v), (u32x4_t*)(gbase + (size_t)(hf * 64 + row) * ld + ch * 8));
;     }
; __device__ void gemm1_phase(const Params& P, int layer, char* smem) {
;     ...
;       if (rope_q) wave_store_rows(wsm, p_qr + (size_t)rowb * DM + cw, DM, acc, lane);
;       else wave_store_rows(wsm, p_proj + (size_t)rowb * INC + cw, INC, acc, lane);
	v_cvt_pk_bf16_f32 v0, v86, v87
	v_cvt_pk_bf16_f32 v1, v72, v73
	v_add_u32_e32 v68, v2, v96
	ds_write_b64 v68, v[0:1]
	v_cvt_pk_bf16_f32 v0, v74, v75
	v_cvt_pk_bf16_f32 v1, v64, v65
	v_add_u32_e32 v69, v2, v118
	ds_write_b64 v69, v[0:1]
	ds_read_b128 v[0:3], v138
	v_or_b32_e32 v74, 8, v147
	v_or_b32_e32 v73, 16, v147
	v_or_b32_e32 v72, 24, v147
	v_lshlrev_b32_e32 v15, 3, v152
	v_lshlrev_b32_e32 v6, 7, v74
	v_lshlrev_b32_e32 v7, 7, v73
	v_lshlrev_b32_e32 v10, 7, v72
	v_add_u32_e32 v66, v139, v6
	v_add_u32_e32 v65, v139, v7
	v_add_u32_e32 v64, v139, v10
	v_lshlrev_b32_e32 v96, 1, v15
	v_cvt_pk_bf16_f32 v22, v60, v61
	v_cvt_pk_bf16_f32 v23, v62, v63
	v_cvt_pk_bf16_f32 v14, v52, v53
	v_cvt_pk_bf16_f32 v15, v50, v51
	v_cvt_pk_bf16_f32 v10, v70, v71
	v_cvt_pk_bf16_f32 v11, v56, v57
	v_cvt_pk_bf16_f32 v6, v58, v59
	v_cvt_pk_bf16_f32 v7, v48, v49
	v_cvt_pk_bf16_f32 v48, v44, v45
	v_cvt_pk_bf16_f32 v49, v46, v47
	v_cvt_pk_bf16_f32 v44, v36, v37
	v_cvt_pk_bf16_f32 v45, v34, v35
	v_cvt_pk_bf16_f32 v36, v54, v55
	v_cvt_pk_bf16_f32 v37, v40, v41
	v_cvt_pk_bf16_f32 v34, v42, v43
	v_cvt_pk_bf16_f32 v35, v32, v33
	v_cvt_pk_bf16_f32 v32, v28, v29
	v_cvt_pk_bf16_f32 v33, v26, v27
	v_cvt_pk_bf16_f32 v28, v142, v143
	v_cvt_pk_bf16_f32 v29, v144, v145
	v_cvt_pk_bf16_f32 v26, v38, v39
	v_cvt_pk_bf16_f32 v27, v24, v25
	v_cvt_pk_bf16_f32 v24, v30, v31
	v_cvt_pk_bf16_f32 v25, v140, v141
	v_cvt_pk_bf16_f32 v12, v4, v5
	v_cvt_pk_bf16_f32 v13, v8, v9
	v_cvt_pk_bf16_f32 v8, v136, v137
	v_cvt_pk_bf16_f32 v9, v16, v17
	v_cvt_pk_bf16_f32 v4, v158, v159
	v_cvt_pk_bf16_f32 v5, v160, v161
	s_and_saveexec_b64 s[0:1], s[4:5]
	s_xor_b64 s[0:1], exec, s[0:1]
	s_cbranch_execz .LBB0_140
	v_mov_b64_e32 v[16:17], s[6:7]
	s_movk_i32 s4, 0x4680
	v_mad_i64_i32 v[16:17], s[4:5], v132, s4, v[16:17]
	v_mov_b32_e32 v131, v97
	v_lshl_add_u64 v[16:17], v[130:131], 1, v[16:17]
	v_mul_u32_u24_e32 v18, 0x2340, v147
	v_lshl_add_u64 v[16:17], v[16:17], 0, v[96:97]
	v_lshlrev_b32_e32 v96, 1, v18
	v_lshl_add_u64 v[18:19], v[16:17], 0, v[96:97]
	s_waitcnt lgkmcnt(0)
	global_store_dwordx4 v[18:19], v[0:3], off nt
	ds_read_b128 v[0:3], v66
	v_add_co_u32_e32 v30, vcc, 0x23000, v18
	v_lshl_add_u32 v38, v147, 7, v139
	s_nop 0
	v_addc_co_u32_e32 v31, vcc, 0, v19, vcc
	s_waitcnt lgkmcnt(0)
	global_store_dwordx4 v[30:31], v[0:3], off offset:1024 nt
	ds_read_b128 v[0:3], v65
	v_add_co_u32_e32 v30, vcc, 0x46000, v18
	s_mov_b32 s4, 0x11a000
	s_nop 0
	v_addc_co_u32_e32 v31, vcc, 0, v19, vcc
	s_waitcnt lgkmcnt(0)
	global_store_dwordx4 v[30:31], v[0:3], off offset:2048 nt
	ds_read_b128 v[0:3], v64
	v_add_co_u32_e32 v30, vcc, 0x69000, v18
	s_nop 1
	v_addc_co_u32_e32 v31, vcc, 0, v19, vcc
	s_waitcnt lgkmcnt(0)
	global_store_dwordx4 v[30:31], v[0:3], off offset:3072 nt
	ds_read_b128 v[0:3], v38 offset:4096
	v_add_u32_e32 v30, 0x8d000, v96
	v_mov_b32_e32 v31, v97
	v_lshl_add_u64 v[30:31], v[16:17], 0, v[30:31]
	s_waitcnt lgkmcnt(0)
	global_store_dwordx4 v[30:31], v[0:3], off nt
	ds_read_b128 v[0:3], v38 offset:5120
	v_add_u32_e32 v30, 0xb0400, v96
	v_mov_b32_e32 v31, v97
	v_lshl_add_u64 v[30:31], v[16:17], 0, v[30:31]
	s_waitcnt lgkmcnt(0)
	global_store_dwordx4 v[30:31], v[0:3], off nt
	ds_read_b128 v[0:3], v38 offset:6144
	v_add_u32_e32 v30, 0xd3800, v96
	v_mov_b32_e32 v31, v97
	v_lshl_add_u64 v[30:31], v[16:17], 0, v[30:31]
	v_add_u32_e32 v96, 0xf6c00, v96
	s_waitcnt lgkmcnt(0)
	global_store_dwordx4 v[30:31], v[0:3], off nt
	ds_read_b128 v[0:3], v38 offset:7168
	v_lshl_add_u64 v[16:17], v[16:17], 0, v[96:97]
	s_waitcnt lgkmcnt(0)
	global_store_dwordx4 v[16:17], v[0:3], off nt
	ds_write2st64_b64 v116, v[22:23], v[48:49] offset1:4
	ds_write2st64_b64 v117, v[14:15], v[44:45] offset1:4
	ds_write2st64_b64 v114, v[10:11], v[36:37] offset1:4
	ds_write2st64_b64 v115, v[6:7], v[34:35] offset1:4
	ds_write_b64 v116, v[32:33] offset:4096
	ds_write_b64 v117, v[28:29] offset:4096
	ds_write_b64 v114, v[26:27] offset:4096
	ds_write_b64 v115, v[24:25] offset:4096
	ds_write_b64 v76, v[20:21]
	ds_write_b64 v67, v[12:13]
	ds_write_b64 v68, v[8:9]
	ds_write_b64 v69, v[4:5]
	ds_read_b128 v[0:3], v138
	v_add_co_u32_e32 v4, vcc, s4, v18
	s_mov_b32 s4, 0x13d000
	s_nop 0
	v_addc_co_u32_e32 v5, vcc, 0, v19, vcc
	s_waitcnt lgkmcnt(0)
	global_store_dwordx4 v[4:5], v[0:3], off nt
	ds_read_b128 v[0:3], v66
	v_add_co_u32_e32 v4, vcc, s4, v18
	s_mov_b32 s4, 0x160000
	s_nop 0
	v_addc_co_u32_e32 v5, vcc, 0, v19, vcc
	s_waitcnt lgkmcnt(0)
	global_store_dwordx4 v[4:5], v[0:3], off offset:1024 nt
	ds_read_b128 v[0:3], v65
	v_add_co_u32_e32 v4, vcc, s4, v18
	s_mov_b32 s4, 0x183000
	s_nop 0
	v_addc_co_u32_e32 v5, vcc, 0, v19, vcc
	s_waitcnt lgkmcnt(0)
	global_store_dwordx4 v[4:5], v[0:3], off offset:2048 nt
	ds_read_b128 v[0:3], v64
	v_add_co_u32_e32 v4, vcc, s4, v18
	s_mov_b32 s4, 0x1a7000
	s_nop 0
	v_addc_co_u32_e32 v5, vcc, 0, v19, vcc
	s_waitcnt lgkmcnt(0)
	global_store_dwordx4 v[4:5], v[0:3], off offset:3072 nt
	ds_read_b128 v[0:3], v38 offset:4096
	v_add_co_u32_e32 v4, vcc, s4, v18
	s_nop 1
	v_addc_co_u32_e32 v5, vcc, 0, v19, vcc
	s_waitcnt lgkmcnt(0)
	global_store_dwordx4 v[4:5], v[0:3], off nt
	ds_read_b128 v[0:3], v38 offset:5120
	v_add_co_u32_e32 v4, vcc, 0x1ca000, v18
	s_nop 1
	v_addc_co_u32_e32 v5, vcc, 0, v19, vcc
	s_waitcnt lgkmcnt(0)
	global_store_dwordx4 v[4:5], v[0:3], off offset:1024 nt
	ds_read_b128 v[0:3], v38 offset:6144
	v_add_co_u32_e32 v4, vcc, 0x1ed000, v18
	s_nop 1
	v_addc_co_u32_e32 v5, vcc, 0, v19, vcc
	s_waitcnt lgkmcnt(0)
	global_store_dwordx4 v[4:5], v[0:3], off offset:2048 nt
	ds_read_b128 v[0:3], v38 offset:7168
	v_add_co_u32_e32 v4, vcc, 0x210000, v18
	s_nop 1
	v_addc_co_u32_e32 v5, vcc, 0, v19, vcc
	s_waitcnt lgkmcnt(0)
	global_store_dwordx4 v[4:5], v[0:3], off offset:3072 nt
; __device__ __forceinline__ uint2 pk4(f32x4 v) { return make_uint2(pk2(v[0], v[1]), pk2(v[2], v[3])); }
; __device__ __forceinline__ void wave_store_rows(char* wsm, u16* gbase, const size_t ld, const f32x4 (&acc)[8][4], const int lane) {
;     ...
;   for (int hf = 0; hf < 2; hf++) {
; #pragma unroll
;     for (int m = 0; m < 4; m++)
; #pragma unroll
;       for (int n = 0; n < 4; n++) {
;         const int row = m * 16 + fr, chunk = n * 2 + (fq >> 1);
;         *(uint2*)(wsm + row * 128 + ((chunk ^ (fr & 7)) << 4) + (fq & 1) * 8) = pk4(acc[hf * 4 + m][n]);
;       }
; #pragma unroll
;     for (int i = 0; i < 8; i++) {
;       const int row = i * 8 + rr;
;       const uint4 v = *(const uint4*)(wsm + row * 128 + ((ch ^ (row & 7)) << 4));
;       __builtin_nontemporal_store(__builtin_bit_cast(u32x4_t, v), (u32x4_t*)(gbase + (size_t)(hf * 64 + row) * ld + ch * 8));
;     }
; __device__ void gemm1_phase(const Params& P, int layer, char* smem) {
;     ...
;       if (rope_q) wave_store_rows(wsm, p_qr + (size_t)rowb * DM + cw, DM, acc, lane);
.LBB0_140:
	s_andn2_saveexec_b64 s[0:1], s[0:1]
	s_cbranch_execz .LBB0_113
	v_lshlrev_b64 v[16:17], 11, v[132:133]
	v_lshl_add_u64 v[16:17], s[2:3], 0, v[16:17]
	v_ashrrev_i32_e32 v131, 31, v130
	v_lshl_add_u64 v[16:17], v[130:131], 1, v[16:17]
	v_lshl_add_u64 v[16:17], v[16:17], 0, v[96:97]
	v_lshlrev_b32_e32 v96, 11, v147
	v_lshl_add_u64 v[18:19], v[16:17], 0, v[96:97]
	s_waitcnt lgkmcnt(0)
	global_store_dwordx4 v[18:19], v[0:3], off nt
	ds_read_b128 v[0:3], v66
	v_lshlrev_b32_e32 v96, 11, v74
	v_lshl_add_u64 v[30:31], v[16:17], 0, v[96:97]
	v_lshlrev_b32_e32 v96, 11, v73
	s_mov_b32 s0, 0x24000
	s_waitcnt lgkmcnt(0)
	global_store_dwordx4 v[30:31], v[0:3], off nt
	ds_read_b128 v[0:3], v65
	v_lshl_add_u64 v[30:31], v[16:17], 0, v[96:97]
	v_lshlrev_b32_e32 v96, 11, v72
	s_waitcnt lgkmcnt(0)
	global_store_dwordx4 v[30:31], v[0:3], off nt
	ds_read_b128 v[0:3], v64
	v_lshl_add_u64 v[30:31], v[16:17], 0, v[96:97]
	s_waitcnt lgkmcnt(0)
	global_store_dwordx4 v[30:31], v[0:3], off nt
	v_or_b32_e32 v30, 32, v147
	v_lshl_add_u32 v38, v30, 7, v139
	ds_read_b128 v[0:3], v38
	v_lshlrev_b32_e32 v96, 11, v30
	v_lshl_add_u64 v[30:31], v[16:17], 0, v[96:97]
	s_waitcnt lgkmcnt(0)
	global_store_dwordx4 v[30:31], v[0:3], off nt
	v_or_b32_e32 v30, 40, v147
	v_lshl_add_u32 v39, v30, 7, v139
	ds_read_b128 v[0:3], v39
	v_lshlrev_b32_e32 v96, 11, v30
	v_lshl_add_u64 v[30:31], v[16:17], 0, v[96:97]
	s_waitcnt lgkmcnt(0)
	global_store_dwordx4 v[30:31], v[0:3], off nt
	v_or_b32_e32 v30, 48, v147
	v_lshl_add_u32 v40, v30, 7, v139
	ds_read_b128 v[0:3], v40
	v_lshlrev_b32_e32 v96, 11, v30
	v_lshl_add_u64 v[30:31], v[16:17], 0, v[96:97]
	s_waitcnt lgkmcnt(0)
	global_store_dwordx4 v[30:31], v[0:3], off nt
	v_or_b32_e32 v30, 56, v147
	v_lshl_add_u32 v31, v30, 7, v139
	ds_read_b128 v[0:3], v31
	v_lshlrev_b32_e32 v96, 11, v30
	v_lshl_add_u64 v[16:17], v[16:17], 0, v[96:97]
	s_waitcnt lgkmcnt(0)
	global_store_dwordx4 v[16:17], v[0:3], off nt
	ds_write2st64_b64 v116, v[22:23], v[48:49] offset1:4
	ds_write2st64_b64 v117, v[14:15], v[44:45] offset1:4
	ds_write2st64_b64 v114, v[10:11], v[36:37] offset1:4
	ds_write2st64_b64 v115, v[6:7], v[34:35] offset1:4
	ds_write_b64 v116, v[32:33] offset:4096
	ds_write_b64 v117, v[28:29] offset:4096
	ds_write_b64 v114, v[26:27] offset:4096
	ds_write_b64 v115, v[24:25] offset:4096
	ds_write_b64 v76, v[20:21]
	ds_write_b64 v67, v[12:13]
	ds_write_b64 v68, v[8:9]
	ds_write_b64 v69, v[4:5]
	ds_read_b128 v[0:3], v138
	v_add_co_u32_e32 v4, vcc, s37, v18
	s_nop 1
	v_addc_co_u32_e32 v5, vcc, 0, v19, vcc
	s_waitcnt lgkmcnt(0)
	global_store_dwordx4 v[4:5], v[0:3], off nt
	ds_read_b128 v[0:3], v66
	v_add_co_u32_e32 v4, vcc, s0, v18
	s_mov_b32 s0, 0x28000
	s_nop 0
	v_addc_co_u32_e32 v5, vcc, 0, v19, vcc
	s_waitcnt lgkmcnt(0)
	global_store_dwordx4 v[4:5], v[0:3], off nt
	ds_read_b128 v[0:3], v65
	v_add_co_u32_e32 v4, vcc, s0, v18
	s_mov_b32 s0, 0x2c000
	s_nop 0
	v_addc_co_u32_e32 v5, vcc, 0, v19, vcc
	s_waitcnt lgkmcnt(0)
	global_store_dwordx4 v[4:5], v[0:3], off nt
	ds_read_b128 v[0:3], v64
	v_add_co_u32_e32 v4, vcc, s0, v18
	s_mov_b32 s0, 0x30000
	s_nop 0
	v_addc_co_u32_e32 v5, vcc, 0, v19, vcc
	s_waitcnt lgkmcnt(0)
	global_store_dwordx4 v[4:5], v[0:3], off nt
	ds_read_b128 v[0:3], v38
	v_add_co_u32_e32 v4, vcc, s0, v18
	s_nop 1
	v_addc_co_u32_e32 v5, vcc, 0, v19, vcc
	s_waitcnt lgkmcnt(0)
	global_store_dwordx4 v[4:5], v[0:3], off nt
	ds_read_b128 v[0:3], v39
	v_add_co_u32_e32 v4, vcc, 0x34000, v18
	s_nop 1
	v_addc_co_u32_e32 v5, vcc, 0, v19, vcc
	s_waitcnt lgkmcnt(0)
	global_store_dwordx4 v[4:5], v[0:3], off nt
	ds_read_b128 v[0:3], v40
	v_add_co_u32_e32 v4, vcc, 0x38000, v18
	s_nop 1
	v_addc_co_u32_e32 v5, vcc, 0, v19, vcc
	s_waitcnt lgkmcnt(0)
	global_store_dwordx4 v[4:5], v[0:3], off nt
	ds_read_b128 v[0:3], v31
	v_add_co_u32_e32 v4, vcc, 0x3c000, v18
	s_nop 1
	v_addc_co_u32_e32 v5, vcc, 0, v19, vcc
	s_waitcnt lgkmcnt(0)
	global_store_dwordx4 v[4:5], v[0:3], off nt
	s_branch .LBB0_113
